# GDN chunk-loop pre-processing trimmed: dead q.k dot removed, plain v_rsq, fma sum of squares, beta reused; prologue pointer loads merged
# speedup vs baseline: 1.0110x; 1.0110x over previous
; #define LAS __attribute__((address_space(3)))
; __device__ __forceinline__ float hload(const f16_t* p) { return (float)(*p); }
; __device__ __forceinline__ float red8(float x) { x = red4(x); x += dppf<0x141>(x); return x; }
; __device__ __forceinline__ void u4f(const u32x4& u, float (&f)[8]) { h2f(u.x, f[0], f[1]); h2f(u.y, f[2], f[3]); h2f(u.z, f[4], f[5]); h2f(u.w, f[6], f[7]); }
; __device__ __forceinline__ void u2f(const u32x2& u, float (&f)[4]) { h2f(u.x, f[0], f[1]); h2f(u.y, f[2], f[3]); }
; template <int MIX, bool SAMPLE>
; __device__ __forceinline__ void rec_load(Raw<MIX>& R, const f16_t* proj, int chunk, int sg, int head, int vcol0) {
;     ...
;     } else if constexpr (MIX == 1) {
;         R.q = *(const u32x4*)(rowp + C_GQKV + head * 64 + cgi * 8);
;         R.k = *(const u32x4*)(rowp + C_GQKV + 256 + head * 64 + cgi * 8);
;         R.v = *(const u32x2*)(rowp + C_GQKV + 512 + head * 64 + vcol0 + cgi * 4);
;         R.ga = hload(rowp + C_GA + head); R.gb = hload(rowp + C_GB + head);
; template <int MIX, bool SAMPLE>
; __device__ __forceinline__ void rec_process(const Raw<MIX>& R, const MixPar& par, int l, LAS float* L, int chunk, int sg, int head) {
;     ...
;         float q[8], k[8], v[4]; u4f(R.q, q); u4f(R.k, k); u2f(R.v, v);
;         float sq = 0.f, sk = 0.f;
; #pragma unroll
;         for (int i = 0; i < 8; ++i) { sq += q[i] * q[i]; sk += k[i] * k[i]; }
;         sq = red8(sq); sk = red8(sk);
;         const float rq = rsqrtf(sq + EPS) * 0.125f, rk = rsqrtf(sk + EPS);
;         float kq = 0.f;
; #pragma unroll
;         for (int i = 0; i < 8; ++i) { q[i] *= rq; k[i] *= rk; kq += q[i] * k[i]; }
;         kq = red8(kq);
;         *(LAS f32x4*)(L + C::OFF_Q + s * 64 + cgi * 8) = (f32x4){q[0], q[1], q[2], q[3]}; *(LAS f32x4*)(L + C::OFF_Q + s * 64 + cgi * 8 + 4) = (f32x4){q[4], q[5], q[6], q[7]};
;         *(LAS f32x4*)(L + C::OFF_K + s * 64 + cgi * 8) = (f32x4){k[0], k[1], k[2], k[3]}; *(LAS f32x4*)(L + C::OFF_K + s * 64 + cgi * 8 + 4) = (f32x4){k[4], k[5], k[6], k[7]};
;         *(LAS f32x4*)(L + C::OFF_V + s * 32 + cgi * 4) = (f32x4){v[0], v[1], v[2], v[3]};
.LBB0_403:
	s_and_b64 vcc, exec, s[4:5]
	s_cbranch_vccz .LBB0_174
	s_mov_b64 s[2:3], s[0:1]
	s_mov_b64 s[4:5], s[0:1]
	s_load_dwordx2 s[2:3], s[2:3], 0xe0
	s_load_dwordx2 s[52:53], s[4:5], 0xe0
	s_waitcnt vmcnt(6)
	v_mov_b32_e32 v10, v202
	s_waitcnt vmcnt(2)
	v_mov_b32_e32 v0, v202
	s_load_dwordx2 s[4:5], s[0:1], 0x68
	s_load_dwordx2 s[8:9], s[0:1], 0x70
	v_readlane_b32 s6, v252, 59
	s_or_b32 s6, s30, s6
	s_lshl_b32 s6, s6, 2
	v_mov_b32_e32 v0, s6
	s_waitcnt lgkmcnt(0)
	global_load_dword v1, v0, s[4:5]
	s_add_u32 s54, s2, 0x5600000
	s_addc_u32 s55, s3, 0
	s_lshl_b32 s10, s31, 11
	s_lshl_b32 s78, s30, 7
	global_load_dword v18, v0, s[8:9]
	s_waitcnt vmcnt(3)
	v_mov_b32_e32 v7, v17
	s_lshl_b32 s56, s30, 1
	s_mov_b32 s57, s79
	v_mov_b32_e32 v11, v202
	s_waitcnt vmcnt(1)
	v_mul_f32_e32 v0, 0x3fb8aa3b, v1
	v_fma_f32 v2, v1, s19, -v0
	v_rndne_f32_e32 v3, v0
	v_fmac_f32_e32 v2, 0x32a5705f, v1
	v_sub_f32_e32 v0, v0, v3
	v_add_f32_e32 v0, v0, v2
	v_exp_f32_e32 v0, v0
	v_cvt_i32_f32_e32 v2, v3
	v_cmp_ngt_f32_e32 vcc, s96, v1
	v_ldexp_f32 v0, v0, v2
	s_nop 0
	v_cndmask_b32_e32 v0, 0, v0, vcc
	v_cmp_nlt_f32_e32 vcc, s97, v1
	s_nop 1
	v_cndmask_b32_e32 v4, v216, v0, vcc
	v_mov_b32_e32 v0, v202
	v_xor_b32_e32 v19, 0x80000000, v4
	v_ashrrev_i32_e32 v1, 3, v0
	v_and_b32_e32 v5, 7, v0
	v_add_u32_e32 v2, s10, v1
	v_mov_b64_e32 v[0:1], s[54:55]
	v_mad_i64_i32 v[2:3], s[2:3], v2, s18, v[0:1]
	v_lshl_add_u64 v[0:1], v[2:3], 0, s[78:79]
	v_lshlrev_b32_e32 v6, 4, v5
	v_lshl_add_u64 v[6:7], v[0:1], 0, v[6:7]
	global_load_dwordx4 v[12:15], v[6:7], off offset:2048
	global_load_dwordx4 v[20:23], v[6:7], off offset:2560
	s_lshl_b32 s78, s34, 6
	v_lshlrev_b32_e32 v16, 3, v5
	v_lshl_add_u64 v[0:1], v[0:1], 0, s[78:79]
	v_lshl_add_u64 v[0:1], v[0:1], 0, v[16:17]
	global_load_dwordx2 v[0:1], v[0:1], off offset:3072
	v_lshl_add_u64 v[2:3], v[2:3], 0, s[56:57]
	v_add_co_u32_e32 v2, vcc, s20, v2
	s_waitcnt vmcnt(2)
	v_cvt_f32_f16_e32 v30, v12
	v_addc_co_u32_e32 v3, vcc, 0, v3, vcc
	global_load_ushort v7, v[2:3], off
	global_load_ushort v5, v[2:3], off offset:8
	v_cvt_f32_f16_sdwa v31, v12 dst_sel:DWORD dst_unused:UNUSED_PAD src0_sel:WORD_1
	s_waitcnt vmcnt(3)
	v_cvt_f32_f16_e32 v38, v20
	v_cvt_f32_f16_sdwa v39, v20 dst_sel:DWORD dst_unused:UNUSED_PAD src0_sel:WORD_1
	v_cvt_f32_f16_e32 v34, v13
	v_cvt_f32_f16_sdwa v35, v13 dst_sel:DWORD dst_unused:UNUSED_PAD src0_sel:WORD_1
	v_cvt_f32_f16_e32 v42, v21
	v_cvt_f32_f16_sdwa v43, v21 dst_sel:DWORD dst_unused:UNUSED_PAD src0_sel:WORD_1
	v_cvt_f32_f16_e32 v8, v14
	v_cvt_f32_f16_sdwa v9, v14 dst_sel:DWORD dst_unused:UNUSED_PAD src0_sel:WORD_1
	v_cvt_f32_f16_e32 v2, v22
	v_cvt_f32_f16_sdwa v3, v22 dst_sel:DWORD dst_unused:UNUSED_PAD src0_sel:WORD_1
	v_pk_mul_f32 v[32:33], v[30:31], v[30:31]
	v_pk_mul_f32 v[40:41], v[38:39], v[38:39]
	v_cvt_f32_f16_e32 v28, v15
	v_cvt_f32_f16_sdwa v29, v15 dst_sel:DWORD dst_unused:UNUSED_PAD src0_sel:WORD_1
	v_pk_mul_f32 v[12:13], v[34:35], v[34:35]
	v_cvt_f32_f16_e32 v36, v23
	v_cvt_f32_f16_sdwa v37, v23 dst_sel:DWORD dst_unused:UNUSED_PAD src0_sel:WORD_1
	v_pk_mul_f32 v[20:21], v[42:43], v[42:43]
	v_mov_b32_e32 v44, v40
	v_mov_b32_e32 v45, v32
	v_mov_b32_e32 v32, v41
	v_pk_add_f32 v[32:33], v[44:45], v[32:33]
	v_mov_b32_e32 v40, v20
	v_mov_b32_e32 v41, v12
	v_pk_mul_f32 v[24:25], v[8:9], v[8:9]
	v_pk_mul_f32 v[26:27], v[2:3], v[2:3]
	v_pk_add_f32 v[32:33], v[40:41], v[32:33]
	v_mov_b32_e32 v12, v21
	v_pk_add_f32 v[12:13], v[12:13], v[32:33]
	v_mov_b32_e32 v20, v26
	v_mov_b32_e32 v21, v24
	v_pk_mul_f32 v[14:15], v[28:29], v[28:29]
	v_pk_mul_f32 v[22:23], v[36:37], v[36:37]
	v_pk_add_f32 v[12:13], v[20:21], v[12:13]
	v_mov_b32_e32 v24, v27
	v_pk_add_f32 v[12:13], v[24:25], v[12:13]
	v_mov_b32_e32 v20, v22
	v_mov_b32_e32 v21, v14
	v_pk_add_f32 v[12:13], v[20:21], v[12:13]
	v_mov_b32_e32 v14, v23
	v_pk_add_f32 v[12:13], v[14:15], v[12:13]
	s_waitcnt vmcnt(2)
	v_cvt_f32_f16_e32 v32, v0
	v_ashrrev_i32_e32 v6, 3, v11
	v_mov_b32_dpp v15, v13 quad_perm:[1,0,3,2] row_mask:0xf bank_mask:0xf bound_ctrl:1
	v_mov_b32_dpp v14, v12 quad_perm:[1,0,3,2] row_mask:0xf bank_mask:0xf bound_ctrl:1
	v_pk_add_f32 v[12:13], v[12:13], v[14:15]
	v_cvt_f32_f16_sdwa v33, v0 dst_sel:DWORD dst_unused:UNUSED_PAD src0_sel:WORD_1
	s_nop 0
	v_mov_b32_dpp v15, v13 quad_perm:[2,3,0,1] row_mask:0xf bank_mask:0xf bound_ctrl:1
	v_mov_b32_dpp v14, v12 quad_perm:[2,3,0,1] row_mask:0xf bank_mask:0xf bound_ctrl:1
	v_pk_add_f32 v[12:13], v[12:13], v[14:15]
	s_nop 1
	v_mov_b32_dpp v15, v13 row_half_mirror row_mask:0xf bank_mask:0xf bound_ctrl:1
	v_mov_b32_dpp v14, v12 row_half_mirror row_mask:0xf bank_mask:0xf bound_ctrl:1
	v_pk_add_f32 v[12:13], v[12:13], v[14:15]
	s_nop 0
	v_pk_add_f32 v[24:25], v[12:13], s[66:67] op_sel_hi:[1,0]
	s_nop 0
	v_mul_f32_e32 v12, 0x4b800000, v25
	v_cmp_gt_f32_e64 s[42:43], s16, v25
	v_cmp_gt_f32_e32 vcc, s16, v24
	s_nop 0
	v_cndmask_b32_e64 v12, v25, v12, s[42:43]
	v_rsq_f32_e32 v12, v12
	s_nop 0
	v_mul_f32_e32 v13, 0x45800000, v12
	v_cndmask_b32_e64 v12, v12, v13, s[42:43]
	v_mul_f32_e32 v16, 0x3e000000, v12
	v_pk_mul_f32 v[20:21], v[16:17], v[8:9] op_sel_hi:[0,1]
	v_mul_f32_e32 v8, 0x4b800000, v24
	v_cndmask_b32_e32 v8, v24, v8, vcc
	v_rsq_f32_e32 v8, v8
	v_pk_mul_f32 v[12:13], v[16:17], v[30:31] op_sel_hi:[0,1]
	v_pk_mul_f32 v[14:15], v[16:17], v[34:35] op_sel_hi:[0,1]
	v_pk_mul_f32 v[22:23], v[16:17], v[28:29] op_sel_hi:[0,1]
	v_mul_f32_e32 v9, 0x45800000, v8
	v_cndmask_b32_e32 v8, v8, v9, vcc
	v_pk_mul_f32 v[24:25], v[8:9], v[38:39] op_sel_hi:[0,1]
	v_pk_mul_f32 v[26:27], v[12:13], v[24:25]
	v_cvt_f32_f16_e32 v34, v1
	v_add_f32_e32 v9, 0, v26
	v_add_f32_e32 v9, v27, v9
	v_pk_mul_f32 v[26:27], v[8:9], v[42:43] op_sel_hi:[0,1]
	v_pk_mul_f32 v[28:29], v[14:15], v[26:27]
	v_cvt_f32_f16_sdwa v35, v1 dst_sel:DWORD dst_unused:UNUSED_PAD src0_sel:WORD_1
	v_add_f32_e32 v9, v28, v9
	v_add_f32_e32 v9, v29, v9
	v_pk_mul_f32 v[28:29], v[8:9], v[2:3] op_sel_hi:[0,1]
	v_pk_mul_f32 v[2:3], v[20:21], v[28:29]
	s_nop 0
	v_add_f32_e32 v2, v2, v9
	v_add_f32_e32 v9, v3, v2
	v_pk_mul_f32 v[30:31], v[8:9], v[36:37] op_sel_hi:[0,1]
	v_pk_mul_f32 v[2:3], v[22:23], v[30:31]
	s_nop 0
	v_add_f32_e32 v2, v2, v9
	v_add_f32_e32 v2, v3, v2
	v_and_b32_e32 v3, 7, v11
	v_cmp_ne_u32_e32 vcc, 0, v3
	v_add_f32_dpp v0, v2, v2 quad_perm:[1,0,3,2] row_mask:0xf bank_mask:0xf bound_ctrl:1
	s_nop 1
	v_add_f32_dpp v1, v0, v0 quad_perm:[2,3,0,1] row_mask:0xf bank_mask:0xf bound_ctrl:1
	v_lshl_add_u32 v0, v6, 8, 0
	v_lshl_add_u32 v8, v3, 5, v0
	ds_write_b128 v8, v[12:15]
	ds_write_b128 v8, v[20:23] offset:16
	ds_write_b128 v8, v[24:27] offset:16384
	ds_write_b128 v8, v[28:31] offset:16400
	v_lshlrev_b32_e32 v8, 7, v6
	v_sub_u32_e32 v0, v0, v8
	v_mov_b32_dpp v2, v1 row_half_mirror row_mask:0xf bank_mask:0xf bound_ctrl:1
	v_lshl_add_u32 v8, v3, 4, v0
	s_waitcnt vmcnt(0)
; #define LAS __attribute__((address_space(3)))
; __device__ __forceinline__ float sigmoidf_(float x) { return 1.0f / (1.0f + __expf(-x)); }
; __device__ __forceinline__ float siluf_(float x) { return x / (1.0f + __expf(-x)); }
; __device__ __forceinline__ float softplusf_(float x) { return x > 20.f ? x : log1pf(expf(x)); }
; template <int MIX, bool SAMPLE>
; __device__ __forceinline__ void rec_process(const Raw<MIX>& R, const MixPar& par, int l, LAS float* L, int chunk, int sg, int head) {
;     ...
;         if (cgi == 0) { const float a = expf(-par.f[0] * softplusf_(R.ga + par.f[1]));
;             *(LAS f32x4*)(L + C::OFF_SC + s * 4) = (f32x4){a, sigmoidf_(R.gb), kq, 0.f}; }
	v_cvt_f32_f16_e32 v60, v5
	v_mul_f32_e32 v60, 0xbfb8aa3b, v60
	v_exp_f32_e32 v60, v60
	s_nop 0
	v_add_f32_e32 v60, 1.0, v60
	v_rcp_f32_e32 v60, v60
	s_nop 0
	v_pk_mul_f32 v[32:33], v[32:33], v[60:61] op_sel_hi:[1,0]
	v_pk_mul_f32 v[34:35], v[34:35], v[60:61] op_sel_hi:[1,0]
	ds_write_b128 v8, v[32:35] offset:32768
	s_and_saveexec_b64 s[2:3], vcc
	s_xor_b64 s[4:5], exec, s[2:3]
	v_xor_b32_e32 v19, 0x80000000, v4
	s_or_saveexec_b64 s[4:5], s[4:5]
	v_readlane_b32 s17, v252, 3
	s_xor_b64 exec, exec, s[4:5]
	s_cbranch_execz .LBB0_410
	s_waitcnt vmcnt(1)
	v_cvt_f32_f16_e32 v3, v7
	v_add_f32_e32 v3, v18, v3
	v_cmp_nlt_f32_e32 vcc, s23, v3
	s_and_saveexec_b64 s[6:7], vcc
	s_cbranch_execz .LBB0_409
	v_mul_f32_e32 v7, 0x3fb8aa3b, v3
	v_rndne_f32_e32 v8, v7
	v_sub_f32_e32 v9, v7, v8
	v_fma_f32 v7, v3, s19, -v7
	v_fmac_f32_e32 v7, 0x32a5705f, v3
	v_add_f32_e32 v7, v9, v7
	v_cvt_i32_f32_e32 v8, v8
	v_exp_f32_e32 v7, v7
	v_cmp_ngt_f32_e32 vcc, s96, v3
	v_ldexp_f32 v7, v7, v8
	s_nop 0
	v_cndmask_b32_e32 v7, 0, v7, vcc
	v_cmp_nlt_f32_e32 vcc, s97, v3
	s_nop 1
	v_cndmask_b32_e32 v3, v216, v7, vcc
	v_add_f32_e32 v7, 1.0, v3
	v_add_f32_e32 v8, -1.0, v7
	v_sub_f32_e32 v9, v8, v7
	v_add_f32_e32 v9, 1.0, v9
	v_sub_f32_e32 v8, v3, v8
	v_add_f32_e32 v11, v8, v9
	v_frexp_mant_f32_e32 v12, v7
	v_cvt_f64_f32_e32 v[8:9], v7
	v_frexp_exp_i32_f64_e32 v8, v[8:9]
	v_cmp_gt_f32_e32 vcc, s62, v12
	s_nop 1
	v_subbrev_co_u32_e32 v16, vcc, 0, v8, vcc
	v_sub_u32_e32 v8, 0, v16
	v_ldexp_f32 v7, v7, v8
	v_ldexp_f32 v8, v11, v8
	v_add_f32_e32 v11, -1.0, v7
	v_add_f32_e32 v9, 1.0, v11
	v_sub_f32_e32 v9, v7, v9
	v_add_f32_e32 v12, v8, v9
	v_add_f32_e32 v9, 1.0, v7
	v_add_f32_e32 v13, -1.0, v9
	v_sub_f32_e32 v7, v7, v13
	v_add_f32_e32 v7, v8, v7
	v_add_f32_e32 v22, v9, v7
	v_rcp_f32_e32 v23, v22
	v_sub_f32_e32 v8, v9, v22
	v_add_f32_e32 v9, v11, v12
	v_add_f32_e32 v7, v7, v8
	v_sub_f32_e32 v8, v11, v9
	v_mul_f32_e32 v24, v9, v23
	v_add_f32_e32 v11, v12, v8
	v_mul_f32_e32 v12, v22, v24
	v_fma_f32 v14, v24, v22, -v12
	v_fmac_f32_e32 v14, v24, v7
	v_add_f32_e32 v8, v12, v14
	v_sub_f32_e32 v13, v9, v8
	v_pk_add_f32 v[20:21], v[8:9], v[12:13] neg_lo:[0,1] neg_hi:[0,1]
	v_mov_b32_e32 v15, v8
	v_pk_add_f32 v[8:9], v[20:21], v[14:15] neg_lo:[0,1] neg_hi:[0,1]
	v_cmp_neq_f32_e32 vcc, s21, v3
	v_add_f32_e32 v9, v11, v9
	v_add_f32_e32 v8, v8, v9
	v_add_f32_e32 v9, v13, v8
	v_mul_f32_e32 v11, v23, v9
	v_mul_f32_e32 v12, v22, v11
	v_fma_f32 v14, v11, v22, -v12
	v_fmac_f32_e32 v14, v11, v7
	v_sub_f32_e32 v7, v13, v9
	v_add_f32_e32 v7, v8, v7
	v_add_f32_e32 v8, v12, v14
	v_sub_f32_e32 v13, v9, v8
	v_pk_add_f32 v[20:21], v[8:9], v[12:13] neg_lo:[0,1] neg_hi:[0,1]
	v_mov_b32_e32 v15, v8
	v_pk_add_f32 v[8:9], v[20:21], v[14:15] neg_lo:[0,1] neg_hi:[0,1]
	s_nop 0
	v_add_f32_e32 v7, v7, v9
	v_add_f32_e32 v7, v8, v7
	v_add_f32_e32 v9, v24, v11
	v_add_f32_e32 v7, v13, v7
	v_sub_f32_e32 v8, v9, v24
	v_mul_f32_e32 v7, v23, v7
	v_sub_f32_e32 v8, v11, v8
	v_add_f32_e32 v7, v8, v7
	v_add_f32_e32 v11, v9, v7
	v_mul_f32_e32 v12, v11, v11
	v_fmamk_f32 v8, v12, 0x3e9b6dac, v204
	v_fmaak_f32 v139, v12, v8, 0x3f2aaada
	v_cvt_f32_i32_e32 v8, v16
	v_sub_f32_e32 v9, v11, v9
	v_sub_f32_e32 v7, v7, v9
	v_mul_f32_e32 v9, v11, v12
	v_pk_mul_f32 v[14:15], v[8:9], v[138:139]
	v_ldexp_f32 v13, v11, 1
	v_fma_f32 v12, v8, s63, -v14
	v_fmac_f32_e32 v12, 0xb102e308, v8
	v_pk_add_f32 v[8:9], v[14:15], v[12:13]
	v_ldexp_f32 v7, v7, 1
	v_sub_f32_e32 v11, v9, v13
	v_sub_f32_e32 v11, v15, v11
	v_add_f32_e32 v21, v7, v11
	v_mov_b32_e32 v20, v14
	v_pk_add_f32 v[14:15], v[8:9], v[14:15] neg_lo:[0,1] neg_hi:[0,1]
	v_pk_add_f32 v[22:23], v[8:9], v[20:21]
	v_mov_b32_e32 v13, v8
	v_mov_b32_e32 v15, v23
	v_pk_add_f32 v[24:25], v[12:13], v[14:15] neg_lo:[0,1] neg_hi:[0,1]
	v_pk_add_f32 v[12:13], v[12:13], v[14:15]
	v_mov_b32_e32 v20, v21
	v_pk_add_f32 v[14:15], v[12:13], v[8:9] op_sel:[1,0] op_sel_hi:[0,1] neg_lo:[0,1] neg_hi:[0,1]
	v_pk_add_f32 v[26:27], v[22:23], v[14:15] op_sel_hi:[1,0] neg_lo:[0,1] neg_hi:[0,1]
	v_mov_b32_e32 v22, v23
	v_mov_b32_e32 v23, v13
	v_pk_mov_b32 v[14:15], v[8:9], v[14:15] op_sel:[1,0]
	v_mov_b32_e32 v21, v8
	v_pk_add_f32 v[14:15], v[22:23], v[14:15] neg_lo:[0,1] neg_hi:[0,1]
	v_mov_b32_e32 v26, v24
	v_pk_add_f32 v[8:9], v[20:21], v[14:15] neg_lo:[0,1] neg_hi:[0,1]
	v_mov_b32_e32 v25, v13
	v_pk_add_f32 v[14:15], v[26:27], v[8:9]
	s_nop 0
	v_pk_add_f32 v[20:21], v[14:15], v[14:15] op_sel:[0,1] op_sel_hi:[1,0]
	s_nop 0
	v_pk_add_f32 v[12:13], v[12:13], v[20:21] op_sel:[1,0] op_sel_hi:[0,1]
	v_mov_b32_e32 v15, v12
	v_pk_add_f32 v[22:23], v[14:15], v[24:25] neg_lo:[0,1] neg_hi:[0,1]
	v_mov_b32_e32 v9, v20
	v_sub_f32_e32 v7, v14, v22
	v_pk_add_f32 v[8:9], v[8:9], v[22:23] neg_lo:[0,1] neg_hi:[0,1]
	v_sub_f32_e32 v7, v24, v7
	v_add_f32_e32 v7, v8, v7
	v_add_f32_e32 v7, v7, v9
	v_add_f32_e32 v7, v12, v7
	v_cndmask_b32_e32 v7, v216, v7, vcc
	v_cmp_lt_f32_e64 vcc, |v3|, s64
	s_nop 1
	v_cndmask_b32_e32 v3, v7, v3, vcc

; #define LAS __attribute__((address_space(3)))
; __device__ __forceinline__ float sigmoidf_(float x) { return 1.0f / (1.0f + __expf(-x)); }
; __device__ __forceinline__ float softplusf_(float x) { return x > 20.f ? x : log1pf(expf(x)); }
; __device__ __forceinline__ float red8(float x) { x = red4(x); x += dppf<0x141>(x); return x; }
; __device__ __forceinline__ void u4f(const u32x4& u, float (&f)[8]) { h2f(u.x, f[0], f[1]); h2f(u.y, f[2], f[3]); h2f(u.z, f[4], f[5]); h2f(u.w, f[6], f[7]); }
; __device__ __forceinline__ void u2f(const u32x2& u, float (&f)[4]) { h2f(u.x, f[0], f[1]); h2f(u.y, f[2], f[3]); }
; template <int MIX, bool SAMPLE>
; __device__ __forceinline__ void rec_process(const Raw<MIX>& R, const MixPar& par, int l, LAS float* L, int chunk, int sg, int head) {
;     ...
;         float q[8], k[8], v[4]; u4f(R.q, q); u4f(R.k, k); u2f(R.v, v);
;         float sq = 0.f, sk = 0.f;
; #pragma unroll
;         for (int i = 0; i < 8; ++i) { sq += q[i] * q[i]; sk += k[i] * k[i]; }
;         sq = red8(sq); sk = red8(sk);
;         const float rq = rsqrtf(sq + EPS) * 0.125f, rk = rsqrtf(sk + EPS);
;         float kq = 0.f;
; #pragma unroll
;         for (int i = 0; i < 8; ++i) { q[i] *= rq; k[i] *= rk; kq += q[i] * k[i]; }
;         kq = red8(kq);
;         *(LAS f32x4*)(L + C::OFF_Q + s * 64 + cgi * 8) = (f32x4){q[0], q[1], q[2], q[3]}; *(LAS f32x4*)(L + C::OFF_Q + s * 64 + cgi * 8 + 4) = (f32x4){q[4], q[5], q[6], q[7]};
;         *(LAS f32x4*)(L + C::OFF_K + s * 64 + cgi * 8) = (f32x4){k[0], k[1], k[2], k[3]}; *(LAS f32x4*)(L + C::OFF_K + s * 64 + cgi * 8 + 4) = (f32x4){k[4], k[5], k[6], k[7]};
;         *(LAS f32x4*)(L + C::OFF_V + s * 32 + cgi * 4) = (f32x4){v[0], v[1], v[2], v[3]};
;         if (cgi == 0) { const float a = expf(-par.f[0] * softplusf_(R.ga + par.f[1]));
;             *(LAS f32x4*)(L + C::OFF_SC + s * 4) = (f32x4){a, sigmoidf_(R.gb), kq, 0.f}; }
.LBB0_413:
	s_or_b64 exec, exec, s[6:7]
	s_add_i32 s2, s12, 1
	s_cmp_lg_u32 s12, 31
	s_cbranch_scc0 .LBB0_420
	s_waitcnt vmcnt(2)
	v_cvt_f32_f16_e32 v23, v23
	v_cvt_f32_f16_e32 v24, v24
	v_cvt_f32_f16_sdwa v31, v0 dst_sel:DWORD dst_unused:UNUSED_PAD src0_sel:WORD_1
	v_cvt_f32_f16_e32 v30, v0
	s_waitcnt vmcnt(1)
	v_cvt_f32_f16_sdwa v47, v4 dst_sel:DWORD dst_unused:UNUSED_PAD src0_sel:WORD_1
	v_cvt_f32_f16_e32 v46, v4
	v_cvt_f32_f16_sdwa v41, v1 dst_sel:DWORD dst_unused:UNUSED_PAD src0_sel:WORD_1
	v_cvt_f32_f16_e32 v40, v1
	v_cvt_f32_f16_sdwa v49, v5 dst_sel:DWORD dst_unused:UNUSED_PAD src0_sel:WORD_1
	v_cvt_f32_f16_e32 v48, v5
	v_cvt_f32_f16_sdwa v15, v2 dst_sel:DWORD dst_unused:UNUSED_PAD src0_sel:WORD_1
	v_cvt_f32_f16_e32 v14, v2
	v_cvt_f32_f16_sdwa v43, v6 dst_sel:DWORD dst_unused:UNUSED_PAD src0_sel:WORD_1
	v_cvt_f32_f16_e32 v42, v6
	v_pk_mul_f32 v[38:39], v[30:31], v[30:31]
	v_pk_mul_f32 v[54:55], v[46:47], v[46:47]
	v_cvt_f32_f16_sdwa v37, v3 dst_sel:DWORD dst_unused:UNUSED_PAD src0_sel:WORD_1
	v_cvt_f32_f16_e32 v36, v3
	v_cvt_f32_f16_sdwa v45, v7 dst_sel:DWORD dst_unused:UNUSED_PAD src0_sel:WORD_1
	v_cvt_f32_f16_e32 v44, v7
	v_pk_fma_f32 v[38:39], v[40:41], v[40:41], v[38:39]
	v_pk_fma_f32 v[54:55], v[48:49], v[48:49], v[54:55]
	v_pk_fma_f32 v[38:39], v[14:15], v[14:15], v[38:39]
	v_pk_fma_f32 v[54:55], v[42:43], v[42:43], v[54:55]
	v_pk_fma_f32 v[38:39], v[36:37], v[36:37], v[38:39]
	v_pk_fma_f32 v[54:55], v[44:45], v[44:45], v[54:55]
	v_add_f32_e32 v29, v38, v39
	v_add_f32_e32 v28, v54, v55
	s_bitcmp1_b32 s2, 0
	s_cselect_b32 s3, 0xe400, 0
	v_mov_b32_dpp v33, v29 quad_perm:[1,0,3,2] row_mask:0xf bank_mask:0xf bound_ctrl:1
	v_mov_b32_dpp v32, v28 quad_perm:[1,0,3,2] row_mask:0xf bank_mask:0xf bound_ctrl:1
	v_pk_add_f32 v[28:29], v[28:29], v[32:33]
	s_add_i32 s3, s3, 0
	s_nop 0
	v_mov_b32_dpp v33, v29 quad_perm:[2,3,0,1] row_mask:0xf bank_mask:0xf bound_ctrl:1
	v_mov_b32_dpp v32, v28 quad_perm:[2,3,0,1] row_mask:0xf bank_mask:0xf bound_ctrl:1
	v_pk_add_f32 v[28:29], v[28:29], v[32:33]
	s_nop 1
	v_mov_b32_dpp v33, v29 row_half_mirror row_mask:0xf bank_mask:0xf bound_ctrl:1
	v_mov_b32_dpp v32, v28 row_half_mirror row_mask:0xf bank_mask:0xf bound_ctrl:1
	v_pk_add_f32 v[28:29], v[28:29], v[32:33]
	s_nop 0
	v_pk_add_f32 v[32:33], v[28:29], s[66:67] op_sel_hi:[1,0]
	v_mov_b32_e32 v29, v202
	s_nop 0
	v_rsq_f32_e32 v16, v33
	v_rsq_f32_e32 v38, v32
	v_ashrrev_i32_e32 v28, 3, v29
	v_mul_f32_e32 v16, 0x3e000000, v16
	v_pk_mul_f32 v[34:35], v[16:17], v[14:15] op_sel_hi:[0,1]
	v_pk_mul_f32 v[30:31], v[16:17], v[30:31] op_sel_hi:[0,1]
	v_pk_mul_f32 v[32:33], v[16:17], v[40:41] op_sel_hi:[0,1]
	v_pk_mul_f32 v[36:37], v[16:17], v[36:37] op_sel_hi:[0,1]
	v_mov_b32_e32 v14, v38
	v_pk_mul_f32 v[38:39], v[14:15], v[46:47] op_sel_hi:[0,1]
	v_pk_mul_f32 v[40:41], v[14:15], v[48:49] op_sel_hi:[0,1]
	v_cvt_f32_f16_sdwa v49, v9 dst_sel:DWORD dst_unused:UNUSED_PAD src0_sel:WORD_1
	v_pk_mul_f32 v[42:43], v[14:15], v[42:43] op_sel_hi:[0,1]
	v_cvt_f32_f16_e32 v48, v9
	v_pk_mul_f32 v[44:45], v[14:15], v[44:45] op_sel_hi:[0,1]
	v_cvt_f32_f16_sdwa v47, v8 dst_sel:DWORD dst_unused:UNUSED_PAD src0_sel:WORD_1
	v_and_b32_e32 v16, 7, v29
	v_cvt_f32_f16_e32 v46, v8
	v_lshlrev_b32_e32 v29, 8, v28
	v_lshlrev_b32_e32 v50, 5, v16
	v_add3_u32 v29, s3, v29, v50
	ds_write_b128 v29, v[30:33]
	ds_write_b128 v29, v[34:37] offset:16
	ds_write_b128 v29, v[38:41] offset:16384
	ds_write_b128 v29, v[42:45] offset:16400
	v_lshlrev_b32_e32 v29, 7, v28
	v_lshlrev_b32_e32 v30, 4, v16
	v_add3_u32 v29, s3, v29, v30
	v_cmp_eq_u32_e32 vcc, 0, v16
	v_mul_f32_e32 v60, 0xbfb8aa3b, v24
	v_exp_f32_e32 v60, v60
	s_nop 0
	v_add_f32_e32 v60, 1.0, v60
	v_rcp_f32_e32 v60, v60
	s_nop 0
	v_pk_mul_f32 v[46:47], v[46:47], v[60:61] op_sel_hi:[1,0]
	v_pk_mul_f32 v[48:49], v[48:49], v[60:61] op_sel_hi:[1,0]
	ds_write_b128 v29, v[46:49] offset:32768
	s_and_saveexec_b64 s[6:7], vcc
	s_cbranch_execz .LBB0_418
	v_add_f32_e32 v16, v18, v23
	v_cmp_nlt_f32_e32 vcc, s23, v16
	s_and_saveexec_b64 s[8:9], vcc
	s_cbranch_execz .LBB0_417
	v_mul_f32_e32 v29, 0x3fb8aa3b, v16
	v_rndne_f32_e32 v30, v29
	v_sub_f32_e32 v31, v29, v30
	v_fma_f32 v29, v16, s19, -v29
	v_fmac_f32_e32 v29, 0x32a5705f, v16
	v_add_f32_e32 v29, v31, v29
	v_cvt_i32_f32_e32 v30, v30
	v_exp_f32_e32 v29, v29
	v_cmp_ngt_f32_e32 vcc, s96, v16
	v_ldexp_f32 v29, v29, v30
	s_nop 0
	v_cndmask_b32_e32 v29, 0, v29, vcc
	v_cmp_nlt_f32_e32 vcc, s97, v16
	s_nop 1
	v_cndmask_b32_e32 v16, v216, v29, vcc
	v_add_f32_e32 v29, 1.0, v16
	v_add_f32_e32 v30, -1.0, v29
	v_log_f32_e32 v31, v29
	v_rcp_f32_e32 v29, v30
	v_cmp_eq_f32_e32 vcc, 0, v30
	v_mul_f32_e32 v31, 0x3f317218, v31
	v_mul_f32_e32 v29, v16, v29
	v_mul_f32_e32 v31, v31, v29
	v_cndmask_b32_e32 v16, v31, v16, vcc
.LBB0_417:
	s_or_b64 exec, exec, s[8:9]
	v_mul_f32_e32 v29, v19, v16
	v_mul_f32_e32 v16, 0x3fb8aa3b, v29
	v_fma_f32 v30, v29, s19, -v16
	v_rndne_f32_e32 v31, v16
	v_fmac_f32_e32 v30, 0x32a5705f, v29
	v_sub_f32_e32 v16, v16, v31
	v_add_f32_e32 v16, v16, v30
	v_exp_f32_e32 v30, v16
	v_cvt_i32_f32_e32 v31, v31
	v_cmp_ngt_f32_e32 vcc, s96, v29
	v_ldexp_f32 v14, v30, v31
	s_nop 0
	v_cndmask_b32_e32 v14, 0, v14, vcc
	v_cmp_nlt_f32_e32 vcc, s97, v29
	v_lshl_add_u32 v28, v28, 4, s3
	s_nop 0
	v_cndmask_b32_e32 v14, v216, v14, vcc
	v_mul_f32_e32 v15, v14, v60
	ds_write_b128 v28, v[14:17] offset:49152
